# attention loop: next K/V fragment read issued right after the MFMA that consumed its register, lgkmcnt(0)->(1) (12 sites)
# speedup vs baseline: 1.0013x; 1.0013x over previous
; __device__ __forceinline__ void finishSM(f32x16& p0, f32x16& p1, float alpha, float& l_reg, bf16x8& pa0, bf16x8& pa1, bf16x8& pa2, bf16x8& pa3) {
;   for (int r = 0; r < 16; ++r) p1[r] = __builtin_amdgcn_exp2f(p1[r]);
;   float ps = 0; for (int r = 0; r < 16; ++r) ps += p0[r]; for (int r = 0; r < 16; ++r) ps += p1[r];
;   { auto rr = __builtin_amdgcn_permlane32_swap(__float_as_uint(ps), __float_as_uint(ps), false, false);
;     ps = __uint_as_float(rr[0]) + __uint_as_float(rr[1]); }
;   l_reg = l_reg * alpha + ps;
;     ...
;   PK4(p0, 0, pa0); PK4(p0, 8, pa1); PK4(p1, 0, pa2); PK4(p1, 8, pa3);
; __device__ __forceinline__ void qkt(f32x16& p0, f32x16& p1, const bf16* Ks, const bf16x8* qr, int r32, int hi) {
;   p0 = f32x16{}; p1 = f32x16{};
;   for (int d0 = 0; d0 < 8; ++d0) { int cb = (d0 * 16 + hi * 8) * 2;
;     bf16x8 b0 = *reinterpret_cast<const bf16x8*>((const char*)Ks + KSWZ(r32, cb));
;     bf16x8 b1 = *reinterpret_cast<const bf16x8*>((const char*)Ks + KSWZ(32 + r32, cb));
;     p0 = __builtin_amdgcn_mfma_f32_32x32x16_bf16(b0, qr[d0], p0, 0, 0, 0);
;     p1 = __builtin_amdgcn_mfma_f32_32x32x16_bf16(b1, qr[d0], p1, 0, 0, 0); }
.LBB0_180:
	ds_read_b128 v[66:69], v212 offset:49152
	ds_read_b128 v[70:73], v212 offset:57344
	ds_read_b128 v[228:231], v217 offset:49152
	ds_read_b128 v[232:235], v217 offset:57344
	v_add_f32_e32 v162, 0, v163
	v_add_f32_e32 v162, v177, v162
	s_waitcnt lgkmcnt(3)
	v_mfma_f32_32x32x16_bf16 v[82:97], v[66:69], v[118:121], 0
	v_add_f32_e32 v162, v164, v162
	v_add_f32_e32 v162, v224, v162
	v_add_f32_e32 v162, v176, v162
	v_add_f32_e32 v162, v227, v162
	v_add_f32_e32 v162, v165, v162
	v_add_f32_e32 v162, v175, v162
	v_add_f32_e32 v162, v166, v162
	s_waitcnt lgkmcnt(2)
	v_mfma_f32_32x32x16_bf16 v[66:81], v[70:73], v[118:121], 0
	v_add_f32_e32 v162, v173, v162
	v_add_f32_e32 v162, v167, v162
	v_add_f32_e32 v162, v174, v162
	v_exp_f32_e32 v160, v160
	v_add_f32_e32 v162, v168, v162
	v_exp_f32_e32 v161, v161
	v_add_f32_e32 v162, v171, v162
	s_waitcnt lgkmcnt(1)
	v_mfma_f32_32x32x16_bf16 v[82:97], v[228:231], v[110:113], v[82:97]
	ds_read_b128 v[228:231], v216 offset:49152
	v_exp_f32_e32 v158, v158
	v_add_f32_e32 v162, v169, v162
	v_exp_f32_e32 v159, v159
	v_add_f32_e32 v162, v172, v162
	v_exp_f32_e32 v154, v154
	v_add_f32_e32 v162, v160, v162
	v_exp_f32_e32 v155, v155
	s_waitcnt lgkmcnt(1)
	v_mfma_f32_32x32x16_bf16 v[66:81], v[232:235], v[110:113], v[66:81]
	ds_read_b128 v[232:235], v216 offset:57344
	v_add_f32_e32 v162, v161, v162
	v_exp_f32_e32 v150, v150
	v_add_f32_e32 v162, v158, v162
	v_exp_f32_e32 v151, v151
	v_add_f32_e32 v162, v159, v162
	v_exp_f32_e32 v148, v148
	s_waitcnt lgkmcnt(1)
	v_mfma_f32_32x32x16_bf16 v[82:97], v[228:231], v[126:129], v[82:97]
	ds_read_b128 v[228:231], v215 offset:49152
	v_add_f32_e32 v162, v154, v162
	v_exp_f32_e32 v149, v149
	v_add_f32_e32 v162, v155, v162
	v_exp_f32_e32 v156, v156
	v_add_f32_e32 v162, v150, v162
	v_exp_f32_e32 v157, v157
	v_add_f32_e32 v162, v151, v162
	s_waitcnt lgkmcnt(1)
	v_mfma_f32_32x32x16_bf16 v[66:81], v[232:235], v[126:129], v[66:81]
	ds_read_b128 v[232:235], v215 offset:57344
	v_exp_f32_e32 v152, v152
	v_add_f32_e32 v162, v148, v162
	v_exp_f32_e32 v153, v153
	v_add_f32_e32 v162, v149, v162
	v_exp_f32_e32 v146, v146
	v_add_f32_e32 v162, v156, v162
	s_waitcnt lgkmcnt(1)
	v_mfma_f32_32x32x16_bf16 v[82:97], v[228:231], v[122:125], v[82:97]
	ds_read_b128 v[228:231], v213 offset:49152
	v_exp_f32_e32 v147, v147
	v_add_f32_e32 v162, v157, v162
	v_add_f32_e32 v162, v152, v162
	v_add_f32_e32 v162, v153, v162
	v_add_f32_e32 v162, v146, v162
	v_add_f32_e32 v221, v147, v162
	v_mov_b32_e32 v222, v221
	s_waitcnt lgkmcnt(1)
	v_mfma_f32_32x32x16_bf16 v[66:81], v[232:235], v[122:125], v[66:81]
	ds_read_b128 v[232:235], v213 offset:57344
	v_permlane32_swap_b32_e32 v221, v222
	s_waitcnt lgkmcnt(1)
	v_mfma_f32_32x32x16_bf16 v[82:97], v[228:231], v[114:117], v[82:97]
	ds_read_b128 v[228:231], v214 offset:49152
	s_waitcnt lgkmcnt(1)
	v_mfma_f32_32x32x16_bf16 v[66:81], v[232:235], v[114:117], v[66:81]
	ds_read_b128 v[232:235], v214 offset:57344
	s_waitcnt lgkmcnt(1)
	v_mfma_f32_32x32x16_bf16 v[82:97], v[228:231], v[106:109], v[82:97]
	ds_read_b128 v[228:231], v219 offset:49152
	s_waitcnt lgkmcnt(1)
	v_mfma_f32_32x32x16_bf16 v[66:81], v[232:235], v[106:109], v[66:81]
	ds_read_b128 v[232:235], v219 offset:57344
	s_waitcnt lgkmcnt(1)
	v_mfma_f32_32x32x16_bf16 v[82:97], v[228:231], v[102:105], v[82:97]
	ds_read_b128 v[228:231], v218 offset:49152
	s_waitcnt lgkmcnt(1)
	v_mfma_f32_32x32x16_bf16 v[66:81], v[232:235], v[102:105], v[66:81]
	ds_read_b128 v[232:235], v218 offset:57344
	v_cvt_pk_bf16_f32 v162, v163, v177
	v_cvt_pk_bf16_f32 v163, v164, v224
	v_cvt_pk_bf16_f32 v164, v176, v227
	v_cvt_pk_bf16_f32 v165, v165, v175
	v_cvt_pk_bf16_f32 v166, v166, v173
	v_cvt_pk_bf16_f32 v167, v167, v174
	s_waitcnt lgkmcnt(1)
	v_mfma_f32_32x32x16_bf16 v[82:97], v[228:231], v[98:101], v[82:97]
	v_permlane32_swap_b32_e32 v162, v164
	v_cvt_pk_bf16_f32 v168, v168, v171
	v_cvt_pk_bf16_f32 v169, v169, v172
	v_cvt_pk_bf16_f32 v172, v160, v161
	v_cvt_pk_bf16_f32 v173, v158, v159
	v_cvt_pk_bf16_f32 v174, v154, v155
	s_waitcnt lgkmcnt(0)
	v_mfma_f32_32x32x16_bf16 v[66:81], v[232:235], v[98:101], v[66:81]
	v_cvt_pk_bf16_f32 v175, v150, v151
	v_cvt_pk_bf16_f32 v224, v148, v149
	v_cvt_pk_bf16_f32 v225, v156, v157
	v_cvt_pk_bf16_f32 v226, v152, v153
	v_cvt_pk_bf16_f32 v227, v146, v147
	v_permlane32_swap_b32_e32 v163, v165
	v_permlane32_swap_b32_e32 v166, v168
	v_permlane32_swap_b32_e32 v167, v169
	v_permlane32_swap_b32_e32 v172, v174
	v_permlane32_swap_b32_e32 v173, v175
	v_permlane32_swap_b32_e32 v224, v226
	v_permlane32_swap_b32_e32 v225, v227
	s_movk_i32 s0, 0xa000
	v_add_co_u32_e32 v146, vcc, s0, v182
	s_movk_i32 s0, 0xc000
	s_nop 0
	v_addc_co_u32_e32 v147, vcc, -1, v183, vcc
	v_add_co_u32_e32 v150, vcc, s0, v182
	s_mov_b32 s0, 0xfeefa000
	s_nop 0
	v_addc_co_u32_e32 v151, vcc, -1, v183, vcc
	v_add_co_u32_e32 v154, vcc, s0, v182
	s_mov_b32 s0, 0xfeefc000
	s_nop 0
	v_addc_co_u32_e32 v155, vcc, -1, v183, vcc
	v_add_co_u32_e32 v158, vcc, s0, v182
	global_load_dwordx4 v[146:149], v[146:147], off
	s_nop 0
	global_load_dwordx4 v[150:153], v[150:151], off
	v_addc_co_u32_e32 v159, vcc, -1, v183, vcc
	global_load_dwordx4 v[154:157], v[154:155], off
	s_nop 0
	global_load_dwordx4 v[158:161], v[158:159], off
	ds_read_b64_tr_b16 v[228:229], v207 offset:0
	ds_read_b64_tr_b16 v[230:231], v207 offset:0x800
	ds_read_b64_tr_b16 v[232:233], v207 offset:0x1000
	ds_read_b64_tr_b16 v[234:235], v207 offset:0x1800
	ds_read_b64_tr_b16 v[236:237], v207 offset:0x2000
	ds_read_b64_tr_b16 v[238:239], v207 offset:0x2800
	ds_read_b64_tr_b16 v[240:241], v207 offset:0x3000
	ds_read_b64_tr_b16 v[242:243], v207 offset:0x3800
	s_waitcnt lgkmcnt(0)
; #define SBAR() __builtin_amdgcn_sched_barrier(0)
; __device__ __forceinline__ void partialSM(f32x16& p0, f32x16& p1, float& m_reg, float& mn, float& alpha) {
;   constexpr float C = SCALE * 1.4426950408889634f;
;   float pmax = p0[0]; for (int r = 1; r < 16; ++r) pmax = fmaxf(pmax, p0[r]); for (int r = 0; r < 16; ++r) pmax = fmaxf(pmax, p1[r]);
;   { auto rr = __builtin_amdgcn_permlane32_swap(__float_as_uint(pmax), __float_as_uint(pmax), false, false);
;     pmax = fmaxf(__uint_as_float(rr[0]), __uint_as_float(rr[1])); }
;   if (__builtin_expect(__all(pmax - m_reg <= THR / SCALE), 1)) { mn = m_reg; alpha = 1.f; }
;   else { mn = fmaxf(m_reg, pmax); alpha = __builtin_amdgcn_exp2f((m_reg - mn) * C); m_reg = mn; }
; template <int OFF> __device__ __forceinline__ s16x4 tr_read(int vb) {
;   s16x4 r; asm volatile("ds_read_b64_tr_b16 %0, %1 offset:%2" : "=&v"(r) : "v"(vb), "i"(OFF) : "memory"); return r;
; }
; template <int D0> __device__ __forceinline__ void pv_one(f32x16& od, int vb, bf16x8 pa0, bf16x8 pa1, bf16x8 pa2, bf16x8 pa3) {
;   const s16x4 l0 = tr_read<v_rd_off(D0, 0, 0)>(vb), h0 = tr_read<v_rd_off(D0, 0, 1)>(vb), l1 = tr_read<v_rd_off(D0, 1, 0)>(vb), h1 = tr_read<v_rd_off(D0, 1, 1)>(vb);
;   const s16x4 l2 = tr_read<v_rd_off(D0, 2, 0)>(vb), h2 = tr_read<v_rd_off(D0, 2, 1)>(vb), l3 = tr_read<v_rd_off(D0, 3, 0)>(vb), h3 = tr_read<v_rd_off(D0, 3, 1)>(vb);
;   asm volatile("s_waitcnt lgkmcnt(0)" ::: "memory"); SBAR();
;     ...
;   od = __builtin_amdgcn_mfma_f32_32x32x16_bf16(pa0, PK(l0, h0), od, 0, 0, 0);
;   od = __builtin_amdgcn_mfma_f32_32x32x16_bf16(pa1, PK(l1, h1), od, 0, 0, 0);
;   od = __builtin_amdgcn_mfma_f32_32x32x16_bf16(pa2, PK(l2, h2), od, 0, 0, 0);
;   od = __builtin_amdgcn_mfma_f32_32x32x16_bf16(pa3, PK(l3, h3), od, 0, 0, 0);
;     ...
; }
; __device__ __forceinline__ void pv_d0(f32x16* o, int vb, bf16x8 pa0, bf16x8 pa1, bf16x8 pa2, bf16x8 pa3) {
;   pv_one<0>(o[0], vb, pa0, pa1, pa2, pa3); pv_one<1>(o[1], vb, pa0, pa1, pa2, pa3); pv_one<2>(o[2], vb, pa0, pa1, pa2, pa3); pv_one<3>(o[3], vb, pa0, pa1, pa2, pa3);
	s_nop 0
	v_mfma_f32_32x32x16_bf16 v[2:17], v[162:165], v[228:231], v[2:17]
	ds_read_b64_tr_b16 v[228:229], v207 offset:0x200
	ds_read_b64_tr_b16 v[230:231], v207 offset:0xa00
	v_mfma_f32_32x32x16_bf16 v[2:17], v[166:169], v[232:235], v[2:17]
	ds_read_b64_tr_b16 v[232:233], v207 offset:0x1200
	ds_read_b64_tr_b16 v[234:235], v207 offset:0x1a00
	v_mfma_f32_32x32x16_bf16 v[2:17], v[172:175], v[236:239], v[2:17]
	ds_read_b64_tr_b16 v[236:237], v207 offset:0x2200
	ds_read_b64_tr_b16 v[238:239], v207 offset:0x2a00
	v_mfma_f32_32x32x16_bf16 v[2:17], v[224:227], v[240:243], v[2:17]
	ds_read_b64_tr_b16 v[240:241], v207 offset:0x3200
	ds_read_b64_tr_b16 v[242:243], v207 offset:0x3a00
	s_waitcnt lgkmcnt(0)
	v_mfma_f32_32x32x16_bf16 v[50:65], v[162:165], v[228:231], v[50:65]
	ds_read_b64_tr_b16 v[228:229], v207 offset:0x400
	ds_read_b64_tr_b16 v[230:231], v207 offset:0xc00
	v_mfma_f32_32x32x16_bf16 v[50:65], v[166:169], v[232:235], v[50:65]
	ds_read_b64_tr_b16 v[232:233], v207 offset:0x1400
	ds_read_b64_tr_b16 v[234:235], v207 offset:0x1c00
	v_mfma_f32_32x32x16_bf16 v[50:65], v[172:175], v[236:239], v[50:65]
	ds_read_b64_tr_b16 v[236:237], v207 offset:0x2400
	ds_read_b64_tr_b16 v[238:239], v207 offset:0x2c00
	v_mfma_f32_32x32x16_bf16 v[50:65], v[224:227], v[240:243], v[50:65]
	ds_read_b64_tr_b16 v[240:241], v207 offset:0x3400
	ds_read_b64_tr_b16 v[242:243], v207 offset:0x3c00
	s_waitcnt lgkmcnt(0)
	v_mfma_f32_32x32x16_bf16 v[34:49], v[162:165], v[228:231], v[34:49]
	ds_read_b64_tr_b16 v[228:229], v207 offset:0x600
	ds_read_b64_tr_b16 v[230:231], v207 offset:0xe00
	v_mfma_f32_32x32x16_bf16 v[34:49], v[166:169], v[232:235], v[34:49]
	ds_read_b64_tr_b16 v[232:233], v207 offset:0x1600
	ds_read_b64_tr_b16 v[234:235], v207 offset:0x1e00
	v_mfma_f32_32x32x16_bf16 v[34:49], v[172:175], v[236:239], v[34:49]
	ds_read_b64_tr_b16 v[236:237], v207 offset:0x2600
	ds_read_b64_tr_b16 v[238:239], v207 offset:0x2e00
	v_mfma_f32_32x32x16_bf16 v[34:49], v[224:227], v[240:243], v[34:49]
	ds_read_b64_tr_b16 v[240:241], v207 offset:0x3600
	ds_read_b64_tr_b16 v[242:243], v207 offset:0x3e00
	s_waitcnt lgkmcnt(0)
	v_mfma_f32_32x32x16_bf16 v[18:33], v[162:165], v[228:231], v[18:33]
	v_max_f32_e32 v162, v83, v83
	v_max_f32_e32 v163, v82, v82
	v_max_f32_e32 v162, v163, v162
	v_max3_f32 v162, v162, v84, v85
	v_max3_f32 v162, v162, v86, v87
	v_max3_f32 v162, v162, v88, v89
	v_max3_f32 v162, v162, v90, v91
	v_max3_f32 v162, v162, v92, v93
	v_max3_f32 v162, v162, v94, v95
	v_mfma_f32_32x32x16_bf16 v[18:33], v[166:169], v[232:235], v[18:33]
	v_max3_f32 v162, v162, v96, v97
	v_max3_f32 v162, v162, v66, v67
	v_max3_f32 v162, v162, v68, v69
	v_max3_f32 v162, v162, v70, v71
	v_max3_f32 v162, v162, v72, v73
	v_max3_f32 v162, v162, v74, v75
	v_max3_f32 v162, v162, v76, v77
	v_max3_f32 v162, v162, v78, v79
	v_mfma_f32_32x32x16_bf16 v[18:33], v[172:175], v[236:239], v[18:33]
	v_max3_f32 v162, v162, v80, v81
	v_mov_b32_e32 v163, v162
	s_nop 1
	v_permlane32_swap_b32_e32 v162, v163
	v_max_f32_e32 v163, v163, v163
	v_max_f32_e32 v162, v162, v162
	v_max_f32_e32 v162, v162, v163
	v_sub_f32_e32 v163, v162, v170
	v_cmp_ge_f32_e32 vcc, s27, v163
	v_max_f32_e32 v163, v170, v170
	v_max_f32_e32 v162, v163, v162
	v_mfma_f32_32x32x16_bf16 v[18:33], v[224:227], v[240:243], v[18:33]
	v_sub_f32_e32 v163, v170, v162
	v_mul_f32_e32 v163, 0x3e0293ee, v163
	v_exp_f32_e32 v163, v163
	s_cmp_eq_u64 vcc, exec
	s_cselect_b64 s[0:1], -1, 0
	s_barrier
	s_waitcnt vmcnt(4)
	v_cndmask_b32_e64 v223, v163, 1.0, s[0:1]
	v_cmp_gt_f32_e32 vcc, 1.0, v223
	s_waitcnt vmcnt(7)
	ds_write_b128 v210, v[130:133]
	s_waitcnt vmcnt(6)
	ds_write_b128 v211, v[138:141]
	s_waitcnt vmcnt(5)
	ds_write_b128 v208, v[134:137] offset:32768
	s_waitcnt vmcnt(4)
	ds_write_b128 v209, v[142:145] offset:32768
	s_cbranch_vccz .LBB0_184
	s_and_saveexec_b64 s[44:45], s[40:41]
	ds_write_b32 v185, v223 offset:128
	s_or_b64 exec, exec, s[44:45]
	s_waitcnt lgkmcnt(0)
	v_add_u32_e32 v163, v181, v0
	ds_read_b128 v[164:167], v163 offset:224
	ds_read_b128 v[172:175], v163 offset:192
	ds_read_b128 v[224:227], v163 offset:160
	ds_read_b128 v[228:231], v163 offset:128
	s_waitcnt lgkmcnt(3)
	v_pk_mul_f32 v[14:15], v[14:15], v[164:165]
	s_waitcnt lgkmcnt(2)
	v_pk_mul_f32 v[10:11], v[10:11], v[172:173]
	s_waitcnt lgkmcnt(1)
	v_pk_mul_f32 v[6:7], v[6:7], v[224:225]
	v_pk_mul_f32 v[16:17], v[16:17], v[166:167]
	v_pk_mul_f32 v[12:13], v[12:13], v[174:175]
	v_pk_mul_f32 v[8:9], v[8:9], v[226:227]
	s_waitcnt lgkmcnt(0)
	v_pk_mul_f32 v[4:5], v[4:5], v[230:231]
	v_pk_mul_f32 v[2:3], v[2:3], v[228:229]
	v_pk_mul_f32 v[62:63], v[62:63], v[164:165]
	v_pk_mul_f32 v[58:59], v[58:59], v[172:173]
	v_pk_mul_f32 v[54:55], v[54:55], v[224:225]
	v_pk_mul_f32 v[64:65], v[64:65], v[166:167]
	v_pk_mul_f32 v[60:61], v[60:61], v[174:175]
	v_pk_mul_f32 v[56:57], v[56:57], v[226:227]
	v_pk_mul_f32 v[52:53], v[52:53], v[230:231]
	v_pk_mul_f32 v[50:51], v[50:51], v[228:229]
	v_pk_mul_f32 v[46:47], v[46:47], v[164:165]
	v_pk_mul_f32 v[42:43], v[42:43], v[172:173]
	v_pk_mul_f32 v[38:39], v[38:39], v[224:225]
	v_pk_mul_f32 v[48:49], v[48:49], v[166:167]
	v_pk_mul_f32 v[44:45], v[44:45], v[174:175]
	v_pk_mul_f32 v[40:41], v[40:41], v[226:227]
	v_pk_mul_f32 v[36:37], v[36:37], v[230:231]
	v_pk_mul_f32 v[34:35], v[34:35], v[228:229]
	v_pk_mul_f32 v[30:31], v[30:31], v[164:165]
	v_pk_mul_f32 v[26:27], v[26:27], v[172:173]
	v_pk_mul_f32 v[22:23], v[22:23], v[224:225]
	v_pk_mul_f32 v[32:33], v[32:33], v[166:167]
	v_pk_mul_f32 v[28:29], v[28:29], v[174:175]
	v_pk_mul_f32 v[24:25], v[24:25], v[226:227]
	v_pk_mul_f32 v[20:21], v[20:21], v[230:231]
	v_pk_mul_f32 v[18:19], v[18:19], v[228:229]
; #define SBAR() __builtin_amdgcn_sched_barrier(0)
; #define SLOAD(i, k0) do { sr_[i].vs0 = St::ld8(&Vh[(long)((k0) + sr) * LDK + sc]); sr_[i].vs1 = St::ld8(&Vh[(long)((k0) + 32 + sr) * LDK + sc]); \
;     sr_[i].ks0 = St::ld8(&Kh[(long)((k0) + sr) * LDK + sc]); sr_[i].ks1 = St::ld8(&Kh[(long)((k0) + 32 + sr) * LDK + sc]); } while (0)
; __device__ __forceinline__ void partialSM(f32x16& p0, f32x16& p1, float& m_reg, float& mn, float& alpha) {
;     ...
;   for (int r = 0; r < 16; ++r) p0[r] = fmaf(p0[r], C, mnC); for (int r = 0; r < 16; ++r) p1[r] = fmaf(p1[r], C, mnC);
;   for (int r = 0; r < 16; ++r) p0[r] = __builtin_amdgcn_exp2f(p0[r]);
; }
; __device__ __forceinline__ void finishSM(f32x16& p0, f32x16& p1, float alpha, float& l_reg, bf16x8& pa0, bf16x8& pa1, bf16x8& pa2, bf16x8& pa3) {
;   for (int r = 0; r < 16; ++r) p1[r] = __builtin_amdgcn_exp2f(p1[r]);
;   float ps = 0; for (int r = 0; r < 16; ++r) ps += p0[r]; for (int r = 0; r < 16; ++r) ps += p1[r];
;   { auto rr = __builtin_amdgcn_permlane32_swap(__float_as_uint(ps), __float_as_uint(ps), false, false);
;     ps = __uint_as_float(rr[0]) + __uint_as_float(rr[1]); }
;   l_reg = l_reg * alpha + ps;
;     ...
;   PK4(p0, 0, pa0); PK4(p0, 8, pa1); PK4(p1, 0, pa2); PK4(p1, 8, pa3);
;     ...
; }
; __device__ __forceinline__ void qkt(f32x16& p0, f32x16& p1, const bf16* Ks, const bf16x8* qr, int r32, int hi) {
;   p0 = f32x16{}; p1 = f32x16{};
;   for (int d0 = 0; d0 < 8; ++d0) { int cb = (d0 * 16 + hi * 8) * 2;
;     bf16x8 b0 = *reinterpret_cast<const bf16x8*>((const char*)Ks + KSWZ(r32, cb));
;     bf16x8 b1 = *reinterpret_cast<const bf16x8*>((const char*)Ks + KSWZ(32 + r32, cb));
;     p0 = __builtin_amdgcn_mfma_f32_32x32x16_bf16(b0, qr[d0], p0, 0, 0, 0);
;     p1 = __builtin_amdgcn_mfma_f32_32x32x16_bf16(b1, qr[d0], p1, 0, 0, 0); }
; template <typename TQ>
; __device__ __forceinline__ void attn_dense_body(const TQ* __restrict__ Qb, const bf16* __restrict__ Kh, const bf16* __restrict__ Vh,
;                                                 bf16* __restrict__ Ob, int seq, char* lds) {
;     ...
;     RESC(alB); __syncthreads();
;     SBAR(); qkt(pA0, pA1, K_lds, qr, r32, hi);
;     finishSM(pB0, pB1, alB, l_reg, pa0, pa1, pa2, pa3); SBAR();
;     if (SDEPTH == 1 || j + 3 < NT) SLOAD(SE, (j + 1 + SDEPTH) * KVBLK); SBAR();
.LBB0_184:
	v_cndmask_b32_e64 v224, v162, v170, s[0:1]
	v_mul_f32_e32 v225, 0xbe0293ee, v224
	v_fmamk_f32 v82, v82, 0x3e0293ee, v225
	v_fmamk_f32 v83, v83, 0x3e0293ee, v225
	v_fmamk_f32 v84, v84, 0x3e0293ee, v225
	v_fmamk_f32 v85, v85, 0x3e0293ee, v225
	v_fmamk_f32 v86, v86, 0x3e0293ee, v225
	v_fmamk_f32 v87, v87, 0x3e0293ee, v225
	v_fmamk_f32 v88, v88, 0x3e0293ee, v225
	v_fmamk_f32 v89, v89, 0x3e0293ee, v225
	v_fmamk_f32 v90, v90, 0x3e0293ee, v225
	v_fmamk_f32 v91, v91, 0x3e0293ee, v225
	v_fmamk_f32 v92, v92, 0x3e0293ee, v225
	v_fmamk_f32 v93, v93, 0x3e0293ee, v225
	v_fmamk_f32 v94, v94, 0x3e0293ee, v225
	v_fmamk_f32 v95, v95, 0x3e0293ee, v225
	v_fmamk_f32 v96, v96, 0x3e0293ee, v225
	v_fmamk_f32 v97, v97, 0x3e0293ee, v225
	v_exp_f32_e32 v162, v82
	v_exp_f32_e32 v177, v83
	v_exp_f32_e32 v163, v84
	v_exp_f32_e32 v176, v85
	v_exp_f32_e32 v164, v86
	v_exp_f32_e32 v175, v87
	v_exp_f32_e32 v165, v88
	v_exp_f32_e32 v174, v89
	v_exp_f32_e32 v166, v90
	v_exp_f32_e32 v173, v91
	v_exp_f32_e32 v167, v92
	v_exp_f32_e32 v172, v93
	v_exp_f32_e32 v168, v94
	v_exp_f32_e32 v171, v95
	v_exp_f32_e32 v169, v96
	v_exp_f32_e32 v170, v97
	v_fmamk_f32 v234, v66, 0x3e0293ee, v225
	v_fmamk_f32 v235, v67, 0x3e0293ee, v225
	v_fmamk_f32 v236, v68, 0x3e0293ee, v225
	v_fmamk_f32 v237, v69, 0x3e0293ee, v225
	v_fmamk_f32 v238, v70, 0x3e0293ee, v225
	v_fmamk_f32 v227, v71, 0x3e0293ee, v225
	v_fmamk_f32 v228, v72, 0x3e0293ee, v225
	v_fmamk_f32 v229, v73, 0x3e0293ee, v225
	v_fmamk_f32 v230, v74, 0x3e0293ee, v225
	v_fmamk_f32 v231, v75, 0x3e0293ee, v225
	v_fmamk_f32 v232, v76, 0x3e0293ee, v225
	v_fmamk_f32 v233, v77, 0x3e0293ee, v225
	v_fmamk_f32 v226, v78, 0x3e0293ee, v225
	v_fmamk_f32 v239, v79, 0x3e0293ee, v225
	v_fmamk_f32 v240, v80, 0x3e0293ee, v225
	v_fmac_f32_e32 v225, 0x3e0293ee, v81
	s_waitcnt lgkmcnt(0)
	s_barrier
	ds_read_b128 v[66:69], v212 offset:32768
	ds_read_b128 v[70:73], v212 offset:40960
	ds_read_b128 v[242:245], v217 offset:32768
	ds_read_b128 v[246:249], v217 offset:40960
	v_exp_f32_e32 v194, v234
	v_exp_f32_e32 v234, v238
	s_waitcnt lgkmcnt(3)
	v_mfma_f32_32x32x16_bf16 v[82:97], v[66:69], v[118:121], 0
	v_exp_f32_e32 v238, v225
	v_add_f32_e32 v225, 0, v162
	v_add_f32_e32 v225, v177, v225
	v_add_f32_e32 v225, v163, v225
	v_add_f32_e32 v225, v176, v225
	v_add_f32_e32 v225, v164, v225
	v_add_f32_e32 v225, v175, v225
	s_waitcnt lgkmcnt(2)
	v_mfma_f32_32x32x16_bf16 v[66:81], v[70:73], v[118:121], 0
	v_add_f32_e32 v225, v165, v225
	v_add_f32_e32 v225, v174, v225
	v_add_f32_e32 v225, v166, v225
	v_add_f32_e32 v225, v173, v225
	v_add_f32_e32 v225, v167, v225
	v_add_f32_e32 v225, v172, v225
	v_add_f32_e32 v225, v168, v225
	s_waitcnt lgkmcnt(1)
	v_mfma_f32_32x32x16_bf16 v[82:97], v[242:245], v[110:113], v[82:97]
	ds_read_b128 v[242:245], v216 offset:32768
	v_exp_f32_e32 v195, v235
	v_add_f32_e32 v225, v171, v225
	v_exp_f32_e32 v200, v236
	v_add_f32_e32 v225, v169, v225
	v_exp_f32_e32 v201, v237
	v_add_f32_e32 v225, v170, v225
	v_add_f32_e32 v225, v194, v225
	s_waitcnt lgkmcnt(1)
	v_mfma_f32_32x32x16_bf16 v[66:81], v[246:249], v[110:113], v[66:81]
	ds_read_b128 v[246:249], v216 offset:40960
	v_exp_f32_e32 v227, v227
	v_add_f32_e32 v225, v195, v225
	v_exp_f32_e32 v228, v228
	v_add_f32_e32 v225, v200, v225
	v_exp_f32_e32 v229, v229
	v_add_f32_e32 v225, v201, v225
	s_waitcnt lgkmcnt(1)
	v_mfma_f32_32x32x16_bf16 v[82:97], v[242:245], v[126:129], v[82:97]
	ds_read_b128 v[242:245], v215 offset:32768
	v_exp_f32_e32 v230, v230
	v_add_f32_e32 v225, v234, v225
	v_exp_f32_e32 v231, v231
	v_add_f32_e32 v225, v227, v225
	v_exp_f32_e32 v232, v232
	v_add_f32_e32 v225, v228, v225
	v_exp_f32_e32 v233, v233
	s_waitcnt lgkmcnt(1)
	v_mfma_f32_32x32x16_bf16 v[66:81], v[246:249], v[126:129], v[66:81]
	ds_read_b128 v[246:249], v215 offset:40960
	v_add_f32_e32 v225, v229, v225
	v_exp_f32_e32 v235, v226
	v_add_f32_e32 v225, v230, v225
	v_exp_f32_e32 v236, v239
	v_add_f32_e32 v225, v231, v225
	v_exp_f32_e32 v237, v240
	s_waitcnt lgkmcnt(1)
	v_mfma_f32_32x32x16_bf16 v[82:97], v[242:245], v[122:125], v[82:97]
	ds_read_b128 v[242:245], v213 offset:32768
	v_add_f32_e32 v225, v232, v225
	v_add_f32_e32 v225, v233, v225
	v_add_f32_e32 v225, v235, v225
	v_add_f32_e32 v225, v236, v225
	v_add_f32_e32 v225, v237, v225
	v_add_f32_e32 v225, v238, v225
	v_mov_b32_e32 v226, v225
	s_waitcnt lgkmcnt(1)
	v_mfma_f32_32x32x16_bf16 v[66:81], v[246:249], v[122:125], v[66:81]
	ds_read_b128 v[246:249], v213 offset:40960
	v_permlane32_swap_b32_e32 v225, v226
	s_waitcnt lgkmcnt(1)
	v_mfma_f32_32x32x16_bf16 v[82:97], v[242:245], v[114:117], v[82:97]
	ds_read_b128 v[242:245], v214 offset:32768
	s_waitcnt lgkmcnt(1)
	v_mfma_f32_32x32x16_bf16 v[66:81], v[246:249], v[114:117], v[66:81]
	ds_read_b128 v[246:249], v214 offset:40960
	s_waitcnt lgkmcnt(1)
	v_mfma_f32_32x32x16_bf16 v[82:97], v[242:245], v[106:109], v[82:97]
	ds_read_b128 v[242:245], v219 offset:32768
	s_waitcnt lgkmcnt(1)
	v_mfma_f32_32x32x16_bf16 v[66:81], v[246:249], v[106:109], v[66:81]
	ds_read_b128 v[246:249], v219 offset:40960
	s_waitcnt lgkmcnt(1)
	v_mfma_f32_32x32x16_bf16 v[82:97], v[242:245], v[102:105], v[82:97]
	ds_read_b128 v[242:245], v218 offset:32768
	s_waitcnt lgkmcnt(1)
	v_mfma_f32_32x32x16_bf16 v[66:81], v[246:249], v[102:105], v[66:81]
	ds_read_b128 v[246:249], v218 offset:40960
	v_cvt_pk_bf16_f32 v162, v162, v177
	v_cvt_pk_bf16_f32 v163, v163, v176
	v_cvt_pk_bf16_f32 v164, v164, v175
	v_cvt_pk_bf16_f32 v165, v165, v174
	v_cvt_pk_bf16_f32 v166, v166, v173
	v_cvt_pk_bf16_f32 v167, v167, v172
	s_waitcnt lgkmcnt(1)
	v_mfma_f32_32x32x16_bf16 v[82:97], v[242:245], v[98:101], v[82:97]
	v_cvt_pk_bf16_f32 v168, v168, v171
	v_cvt_pk_bf16_f32 v169, v169, v170
	v_cvt_pk_bf16_f32 v170, v194, v195
	v_cvt_pk_bf16_f32 v171, v200, v201
	v_cvt_pk_bf16_f32 v172, v234, v227
	v_cvt_pk_bf16_f32 v173, v228, v229
	v_cvt_pk_bf16_f32 v174, v230, v231
	s_waitcnt lgkmcnt(0)
	v_mfma_f32_32x32x16_bf16 v[66:81], v[246:249], v[98:101], v[66:81]
	v_cvt_pk_bf16_f32 v175, v232, v233
	v_cvt_pk_bf16_f32 v176, v235, v236
	v_cvt_pk_bf16_f32 v177, v237, v238
	v_permlane32_swap_b32_e32 v162, v164
	v_permlane32_swap_b32_e32 v163, v165
	v_permlane32_swap_b32_e32 v166, v168
	v_permlane32_swap_b32_e32 v167, v169
	v_permlane32_swap_b32_e32 v170, v172
	v_permlane32_swap_b32_e32 v171, v173
	v_permlane32_swap_b32_e32 v174, v176
	v_permlane32_swap_b32_e32 v175, v177
	s_cmp_ge_u32 s19, s48
	s_cselect_b64 s[44:45], -1, 0
	s_and_b64 vcc, exec, s[44:45]
	s_cbranch_vccnz .LBB0_186
	v_add_co_u32_e32 v130, vcc, 0xffffe000, v182
	s_nop 1
	v_addc_co_u32_e32 v131, vcc, -1, v183, vcc
	v_add_co_u32_e32 v134, vcc, 0xfeefe000, v182
	s_nop 1
	v_addc_co_u32_e32 v135, vcc, -1, v183, vcc
	v_add_co_u32_e32 v142, vcc, 0xfef00000, v182
	global_load_dwordx4 v[130:133], v[130:131], off
	s_nop 0
	global_load_dwordx4 v[134:137], v[134:135], off
	v_addc_co_u32_e32 v143, vcc, -1, v183, vcc
	global_load_dwordx4 v[138:141], v[182:183], off
	s_nop 0
	global_load_dwordx4 v[142:145], v[142:143], off
